# ret+mamba S2 tails: GI row reads hoisted to the start of S2 (mamba both quads, ret first quad)
# speedup vs baseline: 1.0004x; 1.0004x over previous
; __device__ __forceinline__ unsigned cvt_pk_bf16(float lo, float hi) { unsigned r; asm("v_cvt_pk_bf16_f32 %0, %1, %2" : "=v"(r) : "v"(lo), "v"(hi)); return r; }
; template <int DK, int DV, bool SEPQ> ...
;     ...
;         const float gi_i = GI[16 * m + fr];
;         const int n0 = 2 * hw, n1 = 2 * hw + 1; const bool do0 = n0 <= m, do1 = n1 <= m;
;         f32x4 acc0 = {0.f, 0.f, 0.f, 0.f}, acc1 = {0.f, 0.f, 0.f, 0.f};
; #pragma unroll
;         for (int vt = 0; vt < NVTW; ++vt) O[vt] = (f32x4){0.f, 0.f, 0.f, 0.f};
; #pragma unroll
;         for (int ks = 0; ks < DK / 32; ++ks) {
;             const bf16x8 qf = *(const bf16x8*)(QA + (16 * m + fr) * LQ + 32 * ks + 8 * fq);
;             if (do0) { const bf16x8 kf = *(const bf16x8*)(KB + (16 * n0 + fr) * LQ + 32 * ks + 8 * fq); acc0 = __builtin_amdgcn_mfma_f32_16x16x32_bf16(kf, qf, acc0, 0, 0, 0); }
;             if (do1) { const bf16x8 kf = *(const bf16x8*)(KB + (16 * n1 + fr) * LQ + 32 * ks + 8 * fq); acc1 = __builtin_amdgcn_mfma_f32_16x16x32_bf16(kf, qf, acc1, 0, 0, 0); }
;             bf16x8 qs = qf; if (SEPQ) qs = *(const bf16x8*)(QS + (16 * m + fr) * LQ + 32 * ks + 8 * fq);
; #pragma unroll
; __device__ __forceinline__ void ret_block(ArgsP a_, unsigned char* smem) { const ArgsP a = a_;
;     ...
;         { const int cp = tid & 127, jq = tid >> 7;
;           float dj[16];
; #pragma unroll
;           for (int q4 = 0; q4 < 4; ++q4) { const f32x4 t = *(const f32x4*)(DECJ + 16 * jq + 4 * q4); dj[4 * q4] = t[0]; dj[4 * q4 + 1] = t[1]; dj[4 * q4 + 2] = t[2]; dj[4 * q4 + 3] = t[3]; }
;           unsigned lo[8], hi[8];
; #pragma unroll
;           for (int e = 0; e < 8; ++e) { const int j = 16 * jq + 2 * e; const unsigned w0 = *(const unsigned*)(KB + j * LQ + 2 * cp), w1 = *(const unsigned*)(KB + (j + 1) * LQ + 2 * cp);
;               lo[e] = cvt_pk_bf16(__uint_as_float(w0 << 16) * dj[2 * e], __uint_as_float(w1 << 16) * dj[2 * e + 1]);
;               hi[e] = cvt_pk_bf16(__uint_as_float(w0 & 0xffff0000u) * dj[2 * e], __uint_as_float(w1 & 0xffff0000u) * dj[2 * e + 1]); }
;           *(u32x4*)(KT + (2 * cp) * LJ + 16 * jq) = (u32x4){lo[0], lo[1], lo[2], lo[3]}; *(u32x4*)(KT + (2 * cp) * LJ + 16 * jq + 8) = (u32x4){lo[4], lo[5], lo[6], lo[7]};
;           *(u32x4*)(KT + (2 * cp + 1) * LJ + 16 * jq) = (u32x4){hi[0], hi[1], hi[2], hi[3]}; *(u32x4*)(KT + (2 * cp + 1) * LJ + 16 * jq + 8) = (u32x4){hi[4], hi[5], hi[6], hi[7]}; }
.LBB0_269:
	ds_read_b128 v[214:217], v142
	ds_read_b128 v[218:221], v142 offset:16
	ds_read_b128 v[222:225], v142 offset:32
	ds_read_b128 v[226:229], v142 offset:48
	ds_read_b32 v230, v140 offset:33792
	ds_read_b32 v231, v141 offset:34320
	ds_read_b32 v232, v140 offset:34848
	ds_read_b32 v233, v141 offset:35376
	ds_read_b32 v234, v140 offset:35904
	ds_read_b32 v235, v141 offset:36432
	ds_read_b32 v236, v140 offset:36960
	ds_read_b32 v237, v141 offset:37488
	ds_read_b32 v238, v140 offset:38016
	ds_read_b32 v239, v141 offset:38544
	ds_read_b32 v240, v140 offset:39072
	s_waitcnt lgkmcnt(10)
	v_lshlrev_b32_e32 v19, 16, v230
	ds_read_b32 v241, v141 offset:39600
	ds_read_b32 v242, v140 offset:40128
	ds_read_b32 v243, v141 offset:40656
	ds_read_b32 v244, v140 offset:41184
	ds_read_b32 v245, v141 offset:41712
	s_waitcnt lgkmcnt(14)
	v_lshlrev_b32_e32 v80, 16, v231
	v_and_b32_e32 v16, 0xffff0000, v230
	v_and_b32_e32 v18, 0xffff0000, v231
	v_mul_f32_e32 v16, v214, v16
	v_mul_f32_e32 v18, v215, v18
	v_mul_f32_e32 v19, v214, v19
	v_cvt_pk_bf16_f32 v72, v16, v18
	v_mul_f32_e32 v80, v215, v80
	v_cvt_pk_bf16_f32 v80, v19, v80
	s_waitcnt lgkmcnt(13)
	v_lshlrev_b32_e32 v19, 16, v232
	s_waitcnt lgkmcnt(12)
	v_lshlrev_b32_e32 v73, 16, v233
	v_and_b32_e32 v16, 0xffff0000, v232
	v_and_b32_e32 v18, 0xffff0000, v233
	v_mul_f32_e32 v73, v217, v73
	v_mul_f32_e32 v16, v216, v16
	v_mul_f32_e32 v18, v217, v18
	v_mul_f32_e32 v19, v216, v19
	v_cvt_pk_bf16_f32 v81, v19, v73
	v_cvt_pk_bf16_f32 v73, v16, v18
	s_waitcnt lgkmcnt(11)
	v_lshlrev_b32_e32 v19, 16, v234
	s_waitcnt lgkmcnt(10)
	v_lshlrev_b32_e32 v74, 16, v235
	v_and_b32_e32 v16, 0xffff0000, v234
	v_and_b32_e32 v18, 0xffff0000, v235
	v_mul_f32_e32 v74, v219, v74
	v_mul_f32_e32 v16, v218, v16
	v_mul_f32_e32 v18, v219, v18
	v_mul_f32_e32 v19, v218, v19
	v_cvt_pk_bf16_f32 v82, v19, v74
	v_cvt_pk_bf16_f32 v74, v16, v18
	s_waitcnt lgkmcnt(9)
	v_lshlrev_b32_e32 v19, 16, v236
	s_waitcnt lgkmcnt(8)
	v_lshlrev_b32_e32 v75, 16, v237
	v_and_b32_e32 v16, 0xffff0000, v236
	v_and_b32_e32 v18, 0xffff0000, v237
	v_mul_f32_e32 v75, v221, v75
	v_mul_f32_e32 v16, v220, v16
	v_mul_f32_e32 v18, v221, v18
	v_mul_f32_e32 v19, v220, v19
	v_cvt_pk_bf16_f32 v83, v19, v75
	v_cvt_pk_bf16_f32 v75, v16, v18
	s_waitcnt lgkmcnt(7)
	v_lshlrev_b32_e32 v19, 16, v238
	s_waitcnt lgkmcnt(6)
	v_lshlrev_b32_e32 v88, 16, v239
	v_and_b32_e32 v16, 0xffff0000, v238
	v_and_b32_e32 v18, 0xffff0000, v239
	v_mul_f32_e32 v16, v222, v16
	v_mul_f32_e32 v18, v223, v18
	v_mul_f32_e32 v19, v222, v19
	v_cvt_pk_bf16_f32 v84, v16, v18
	v_mul_f32_e32 v88, v223, v88
	v_cvt_pk_bf16_f32 v88, v19, v88
	s_waitcnt lgkmcnt(5)
	v_lshlrev_b32_e32 v19, 16, v240
	s_waitcnt lgkmcnt(4)
	v_lshlrev_b32_e32 v85, 16, v241
	v_and_b32_e32 v16, 0xffff0000, v240
	v_and_b32_e32 v18, 0xffff0000, v241
	v_mul_f32_e32 v85, v225, v85
	v_mul_f32_e32 v16, v224, v16
	v_mul_f32_e32 v18, v225, v18
	v_mul_f32_e32 v19, v224, v19
	v_cvt_pk_bf16_f32 v89, v19, v85
	v_cvt_pk_bf16_f32 v85, v16, v18
	s_waitcnt lgkmcnt(3)
	v_lshlrev_b32_e32 v19, 16, v242
	s_waitcnt lgkmcnt(2)
	v_lshlrev_b32_e32 v86, 16, v243
	v_and_b32_e32 v16, 0xffff0000, v242
	v_and_b32_e32 v18, 0xffff0000, v243
	v_mul_f32_e32 v86, v227, v86
	v_mul_f32_e32 v16, v226, v16
	v_mul_f32_e32 v18, v227, v18
	v_mul_f32_e32 v19, v226, v19
	v_cvt_pk_bf16_f32 v90, v19, v86
	v_cvt_pk_bf16_f32 v86, v16, v18
	s_waitcnt lgkmcnt(1)
	v_lshlrev_b32_e32 v19, 16, v244
	s_waitcnt lgkmcnt(0)
	v_lshlrev_b32_e32 v76, 16, v245
	v_and_b32_e32 v16, 0xffff0000, v244
	v_and_b32_e32 v18, 0xffff0000, v245
	v_mul_f32_e32 v19, v228, v19
	v_mul_f32_e32 v16, v228, v16
	v_mul_f32_e32 v18, v229, v18
	v_mul_f32_e32 v76, v229, v76
	v_cvt_pk_bf16_f32 v91, v19, v76
	v_cvt_pk_bf16_f32 v87, v16, v18
	ds_write_b128 v124, v[80:83]
	ds_write_b128 v124, v[88:91] offset:16
	ds_write_b128 v124, v[72:75] offset:144
	ds_write_b128 v124, v[84:87] offset:160
	s_waitcnt lgkmcnt(0)
	ds_read_b128 v[88:91], v128
	ds_read_b32 v92, v125
	ds_read_b128 v[214:217], v126
	ds_read_b128 v[218:221], v127 offset:33792
	ds_read_b128 v[222:225], v127 offset:42240
	ds_read_b128 v[226:229], v165
	ds_read_b128 v[230:233], v165 offset:8448
	ds_read_b128 v[166:169], v126 offset:64
	ds_read_b128 v[170:173], v127 offset:33856
	ds_read_b128 v[174:177], v127 offset:42304
	ds_read_b128 v[178:181], v165 offset:64
	ds_read_b128 v[182:185], v165 offset:8512
	s_waitcnt lgkmcnt(5)
	v_mfma_f32_16x16x32_bf16 v[76:79], v[218:221], v[214:217], 0
	v_mfma_f32_16x16x32_bf16 v[72:75], v[222:225], v[214:217], 0
	v_mfma_f32_16x16x32_bf16 v[80:83], v[226:229], v[214:217], 0
	v_mfma_f32_16x16x32_bf16 v[84:87], v[230:233], v[214:217], 0
	ds_read_b128 v[214:217], v126 offset:128
	ds_read_b128 v[218:221], v127 offset:33920
	ds_read_b128 v[222:225], v127 offset:42368
	ds_read_b128 v[226:229], v165 offset:128
	ds_read_b128 v[230:233], v165 offset:8576
	s_waitcnt lgkmcnt(5)
	v_mfma_f32_16x16x32_bf16 v[76:79], v[170:173], v[166:169], v[76:79]
	v_mfma_f32_16x16x32_bf16 v[72:75], v[174:177], v[166:169], v[72:75]
	v_mfma_f32_16x16x32_bf16 v[80:83], v[178:181], v[166:169], v[80:83]
	v_mfma_f32_16x16x32_bf16 v[84:87], v[182:185], v[166:169], v[84:87]
	ds_read_b128 v[166:169], v126 offset:192
	ds_read_b128 v[170:173], v127 offset:33984
	ds_read_b128 v[174:177], v127 offset:42432
	ds_read_b128 v[178:181], v165 offset:192
	ds_read_b128 v[182:185], v165 offset:8640
	s_waitcnt lgkmcnt(5)
	v_mfma_f32_16x16x32_bf16 v[76:79], v[218:221], v[214:217], v[76:79]
	v_mfma_f32_16x16x32_bf16 v[72:75], v[222:225], v[214:217], v[72:75]
	v_mfma_f32_16x16x32_bf16 v[80:83], v[226:229], v[214:217], v[80:83]
	v_mfma_f32_16x16x32_bf16 v[84:87], v[230:233], v[214:217], v[84:87]
	ds_read_b128 v[214:217], v126 offset:256
	ds_read_b128 v[218:221], v127 offset:34048
	ds_read_b128 v[222:225], v127 offset:42496
	ds_read_b128 v[226:229], v165 offset:256
	ds_read_b128 v[230:233], v165 offset:8704
	s_waitcnt lgkmcnt(5)
; __device__ __forceinline__ unsigned cvt_pk_bf16(float lo, float hi) { unsigned r; asm("v_cvt_pk_bf16_f32 %0, %1, %2" : "=v"(r) : "v"(lo), "v"(hi)); return r; }
; template <int DK, int DV, bool SEPQ> ...
;     ...
;         for (int ks = 0; ks < DK / 32; ++ks) {
;             const bf16x8 qf = *(const bf16x8*)(QA + (16 * m + fr) * LQ + 32 * ks + 8 * fq);
;             if (do0) { const bf16x8 kf = *(const bf16x8*)(KB + (16 * n0 + fr) * LQ + 32 * ks + 8 * fq); acc0 = __builtin_amdgcn_mfma_f32_16x16x32_bf16(kf, qf, acc0, 0, 0, 0); }
;             if (do1) { const bf16x8 kf = *(const bf16x8*)(KB + (16 * n1 + fr) * LQ + 32 * ks + 8 * fq); acc1 = __builtin_amdgcn_mfma_f32_16x16x32_bf16(kf, qf, acc1, 0, 0, 0); }
;             bf16x8 qs = qf; if (SEPQ) qs = *(const bf16x8*)(QS + (16 * m + fr) * LQ + 32 * ks + 8 * fq);
; #pragma unroll
;             for (int vt = 0; vt < NVTW; ++vt) { const bf16x8 sf = *(const bf16x8*)(ST + (16 * (hw * NVTW + vt) + fr) * LQ + 32 * ks + 8 * fq); O[vt] = __builtin_amdgcn_mfma_f32_16x16x32_bf16(sf, qs, O[vt], 0, 0, 0); }
;         }
; #pragma unroll
;         for (int nn = 0; nn < 2; ++nn) {
;             const int n = 2 * hw + nn; const f32x4 acc = nn == 0 ? acc0 : acc1;
;             const f32x4 gj = *(const f32x4*)(GI + 16 * n + 4 * fq); const int i = 16 * m + fr, j0 = 16 * n + 4 * fq; float p[4];
; #pragma unroll
;             for (int e = 0; e < 4; ++e) p[e] = (j0 + e <= i) ? acc[e] * __expf(gi_i - gj[e]) : 0.f;
;             u32x2 w; w.x = cvt_pk_bf16(p[0], p[1]); w.y = cvt_pk_bf16(p[2], p[3]); *(u32x2*)(P + (16 * m + fr) * LJ + j0) = w;
;         }
;         const float ei = __expf(gi_i);
; #pragma unroll
;         for (int vt = 0; vt < NVTW; ++vt) O[vt] = O[vt] * ei;
	v_mfma_f32_16x16x32_bf16 v[76:79], v[170:173], v[166:169], v[76:79]
	v_mfma_f32_16x16x32_bf16 v[72:75], v[174:177], v[166:169], v[72:75]
	v_mfma_f32_16x16x32_bf16 v[80:83], v[178:181], v[166:169], v[80:83]
	v_mfma_f32_16x16x32_bf16 v[84:87], v[182:185], v[166:169], v[84:87]
	ds_read_b128 v[166:169], v126 offset:320
	ds_read_b128 v[170:173], v127 offset:34112
	ds_read_b128 v[174:177], v127 offset:42560
	ds_read_b128 v[178:181], v165 offset:320
	ds_read_b128 v[182:185], v165 offset:8768
	s_waitcnt lgkmcnt(5)
	v_mfma_f32_16x16x32_bf16 v[76:79], v[218:221], v[214:217], v[76:79]
	v_mfma_f32_16x16x32_bf16 v[72:75], v[222:225], v[214:217], v[72:75]
	v_mfma_f32_16x16x32_bf16 v[80:83], v[226:229], v[214:217], v[80:83]
	v_mfma_f32_16x16x32_bf16 v[84:87], v[230:233], v[214:217], v[84:87]
	ds_read_b128 v[214:217], v126 offset:384
	ds_read_b128 v[218:221], v127 offset:34176
	ds_read_b128 v[222:225], v127 offset:42624
	ds_read_b128 v[226:229], v165 offset:384
	ds_read_b128 v[230:233], v165 offset:8832
	s_waitcnt lgkmcnt(5)
	v_mfma_f32_16x16x32_bf16 v[76:79], v[170:173], v[166:169], v[76:79]
	v_mfma_f32_16x16x32_bf16 v[72:75], v[174:177], v[166:169], v[72:75]
	v_mfma_f32_16x16x32_bf16 v[80:83], v[178:181], v[166:169], v[80:83]
	v_mfma_f32_16x16x32_bf16 v[84:87], v[182:185], v[166:169], v[84:87]
	ds_read_b128 v[166:169], v126 offset:448
	ds_read_b128 v[170:173], v127 offset:34240
	ds_read_b128 v[174:177], v127 offset:42688
	ds_read_b128 v[178:181], v165 offset:448
	ds_read_b128 v[182:185], v165 offset:8896
	s_waitcnt lgkmcnt(5)
	v_mfma_f32_16x16x32_bf16 v[76:79], v[218:221], v[214:217], v[76:79]
	v_mfma_f32_16x16x32_bf16 v[72:75], v[222:225], v[214:217], v[72:75]
	v_mfma_f32_16x16x32_bf16 v[80:83], v[226:229], v[214:217], v[80:83]
	v_mfma_f32_16x16x32_bf16 v[84:87], v[230:233], v[214:217], v[84:87]
	s_waitcnt lgkmcnt(0)
	v_mfma_f32_16x16x32_bf16 v[76:79], v[170:173], v[166:169], v[76:79]
	v_mfma_f32_16x16x32_bf16 v[72:75], v[174:177], v[166:169], v[72:75]
	v_mfma_f32_16x16x32_bf16 v[80:83], v[178:181], v[166:169], v[80:83]
	v_mfma_f32_16x16x32_bf16 v[84:87], v[182:185], v[166:169], v[84:87]
	s_nop 7
	v_cmp_gt_i32_e32 vcc, s89, v132
	s_waitcnt lgkmcnt(0)
	v_sub_f32_e32 v16, v92, v88
	v_mul_f32_e32 v16, 0x3fb8aa3b, v16
	v_exp_f32_e32 v16, v16
	v_sub_f32_e32 v18, v92, v89
	v_sub_f32_e32 v19, v92, v90
	v_mul_f32_e32 v18, 0x3fb8aa3b, v18
	v_mul_f32_e32 v16, v76, v16
	v_mul_f32_e32 v19, 0x3fb8aa3b, v19
	v_sub_f32_e32 v76, v92, v91
	v_exp_f32_e32 v18, v18
	v_exp_f32_e32 v19, v19
	v_mul_f32_e32 v76, 0x3fb8aa3b, v76
	v_exp_f32_e32 v76, v76
	v_mul_f32_e32 v18, v77, v18
	v_mul_f32_e32 v19, v78, v19
	v_cndmask_b32_e64 v18, 0, v18, s[50:51]
	v_cndmask_b32_e64 v19, v19, 0, s[52:53]
	v_mul_f32_e32 v76, v79, v76
	v_cndmask_b32_e64 v16, v16, 0, s[48:49]
	v_cndmask_b32_e64 v76, v76, 0, s[54:55]
	v_cvt_pk_bf16_f32 v18, v16, v18
	v_cvt_pk_bf16_f32 v19, v19, v76
	ds_write_b64 v129, v[18:19]
	ds_read_b128 v[76:79], v128 offset:64
	s_waitcnt lgkmcnt(0)
	v_sub_f32_e32 v16, v92, v76
	v_mul_f32_e32 v16, 0x3fb8aa3b, v16
	v_sub_f32_e32 v18, v92, v77
	v_exp_f32_e32 v16, v16
	v_mul_f32_e32 v18, 0x3fb8aa3b, v18
	v_exp_f32_e32 v18, v18
	v_sub_f32_e32 v19, v92, v78
	v_mul_f32_e32 v16, v72, v16
	v_sub_f32_e32 v72, v92, v79
	v_mul_f32_e32 v18, v73, v18
	v_mul_f32_e32 v19, 0x3fb8aa3b, v19
	v_mul_f32_e32 v72, 0x3fb8aa3b, v72
	v_cndmask_b32_e64 v16, v16, 0, s[56:57]
	v_cndmask_b32_e64 v18, 0, v18, s[58:59]
	v_exp_f32_e32 v19, v19
	v_exp_f32_e32 v72, v72
	v_cvt_pk_bf16_f32 v18, v16, v18
	v_mul_f32_e32 v16, 0x3fb8aa3b, v92
	v_exp_f32_e32 v16, v16
	v_mul_f32_e32 v19, v74, v19
	v_mul_f32_e32 v72, v75, v72
	v_cndmask_b32_e64 v19, v19, 0, s[60:61]
	v_cndmask_b32_e64 v72, v72, 0, s[62:63]
	v_cvt_pk_bf16_f32 v19, v19, v72
	ds_write_b64 v129, v[18:19] offset:32
	v_pk_mul_f32 v[72:73], v[16:17], v[80:81] op_sel_hi:[0,1]
	v_pk_mul_f32 v[74:75], v[16:17], v[82:83] op_sel_hi:[0,1]
	v_pk_mul_f32 v[76:77], v[16:17], v[84:85] op_sel_hi:[0,1]
	v_pk_mul_f32 v[78:79], v[16:17], v[86:87] op_sel_hi:[0,1]
	s_waitcnt lgkmcnt(0)
	s_barrier
; __device__ __forceinline__ unsigned cvt_pk_bf16(float lo, float hi) { unsigned r; asm("v_cvt_pk_bf16_f32 %0, %1, %2" : "=v"(r) : "v"(lo), "v"(hi)); return r; }
; template <int DK, int DV, bool SEPQ> ...
;     ...
; #pragma unroll
;     for (int ks = 0; ks < 2; ++ks) { const bf16x8 pf = *(const bf16x8*)(P + (16 * m + fr) * LJ + 32 * ks + 8 * fq);
; #pragma unroll
;         for (int vt = 0; vt < NVTW; ++vt) { const bf16x8 vf = *(const bf16x8*)(VT + (16 * (hw * NVTW + vt) + fr) * LJ + 32 * ks + 8 * fq); O[vt] = __builtin_amdgcn_mfma_f32_16x16x32_bf16(vf, pf, O[vt], 0, 0, 0); } }
; #pragma unroll
;     for (int ct = 0; ct < NCTW; ++ct) { const int ctg = wid * NCTW + ct; const f32x4 dec = *(const f32x4*)(SDEC + 16 * ctg + 4 * fq);
; #pragma unroll
;         for (int vt = 0; vt < NVT; ++vt) S[ct][vt] = S[ct][vt] * dec;
; #pragma unroll
;         for (int ks = 0; ks < 2; ++ks) { const bf16x8 kf = *(const bf16x8*)(KT + (16 * ctg + fr) * LJ + 32 * ks + 8 * fq);
; #pragma unroll
;             for (int vt = 0; vt < NVT; ++vt) { const bf16x8 vf = *(const bf16x8*)(VT2 + (16 * vt + fr) * LJ + 32 * ks + 8 * fq); S[ct][vt] = __builtin_amdgcn_mfma_f32_16x16x32_bf16(kf, vf, S[ct][vt], 0, 0, 0); } } }
; __device__ __forceinline__ void ret_block(ArgsP a_, unsigned char* smem) { const ArgsP a = a_;
;     ...
;         const int m = wid >> 1, hw = wid & 1, i = 16 * m + fr;
;         if (i < len) {
; #pragma unroll
;             for (int vt = 0; vt < 2; ++vt) *(u32x2*)(OB + (size_t)(row0 + i) * 2048 + h * 512 + vs * 64 + 16 * (hw * 2 + vt) + 4 * fq) = (u32x2){cvt_pk_bf16(O[vt][0], O[vt][1]), cvt_pk_bf16(O[vt][2], O[vt][3])}; }
	ds_read_b128 v[214:217], v130
	ds_read_b128 v[218:221], v144
	ds_read_b128 v[222:225], v144 offset:2304
	ds_read_b128 v[226:229], v130 offset:64
	ds_read_b128 v[230:233], v144 offset:64
	ds_read_b128 v[234:237], v144 offset:2368
	ds_read_b128 v[238:241], v131
	ds_read_b128 v[242:245], v145
	ds_read_b128 v[246:249], v147
	ds_read_b128 v[166:169], v147 offset:2304
	ds_read_b128 v[170:173], v147 offset:4608
	ds_read_b128 v[174:177], v147 offset:6912
	ds_read_b128 v[178:181], v145 offset:64
	ds_read_b128 v[182:185], v147 offset:64
	ds_read_b128 v[80:83], v147 offset:2368
	s_waitcnt lgkmcnt(13)
	v_mfma_f32_16x16x32_bf16 v[72:75], v[218:221], v[214:217], v[72:75]
	ds_read_b128 v[84:87], v147 offset:4672
	ds_read_b128 v[88:91], v147 offset:6976
	s_waitcnt lgkmcnt(14)
	v_mfma_f32_16x16x32_bf16 v[76:79], v[222:225], v[214:217], v[76:79]
	ds_read_b128 v[218:221], v131 offset:64
	s_waitcnt lgkmcnt(13)
	v_mfma_f32_16x16x32_bf16 v[72:75], v[230:233], v[226:229], v[72:75]
	ds_read_b128 v[214:217], v164
	ds_read_b128 v[222:225], v164 offset:64
	s_waitcnt lgkmcnt(14)
	v_mfma_f32_16x16x32_bf16 v[76:79], v[234:237], v[226:229], v[76:79]
	s_waitcnt lgkmcnt(13)
	v_pk_mul_f32 v[42:43], v[42:43], v[240:241]
	v_pk_mul_f32 v[40:41], v[40:41], v[238:239]
	v_pk_mul_f32 v[46:47], v[46:47], v[240:241]
	v_pk_mul_f32 v[44:45], v[44:45], v[238:239]
	v_pk_mul_f32 v[50:51], v[50:51], v[240:241]
	v_pk_mul_f32 v[48:49], v[48:49], v[238:239]
	v_pk_mul_f32 v[54:55], v[54:55], v[240:241]
	v_pk_mul_f32 v[52:53], v[52:53], v[238:239]
	s_waitcnt lgkmcnt(11)
	v_mfma_f32_16x16x32_bf16 v[40:43], v[242:245], v[246:249], v[40:43]
	s_waitcnt lgkmcnt(10)
	v_mfma_f32_16x16x32_bf16 v[44:47], v[242:245], v[166:169], v[44:47]
	s_waitcnt lgkmcnt(9)
	v_mfma_f32_16x16x32_bf16 v[48:51], v[242:245], v[170:173], v[48:51]
	s_waitcnt lgkmcnt(8)
	v_mfma_f32_16x16x32_bf16 v[52:55], v[242:245], v[174:177], v[52:55]
	s_waitcnt lgkmcnt(6)
	v_mfma_f32_16x16x32_bf16 v[40:43], v[178:181], v[182:185], v[40:43]
	s_waitcnt lgkmcnt(5)
	v_mfma_f32_16x16x32_bf16 v[44:47], v[178:181], v[80:83], v[44:47]
	s_waitcnt lgkmcnt(4)
	v_mfma_f32_16x16x32_bf16 v[48:51], v[178:181], v[84:87], v[48:51]
	s_waitcnt lgkmcnt(3)
	v_mfma_f32_16x16x32_bf16 v[52:55], v[178:181], v[88:91], v[52:55]
	s_waitcnt lgkmcnt(2)
	v_pk_mul_f32 v[58:59], v[58:59], v[220:221]
	v_pk_mul_f32 v[56:57], v[56:57], v[218:219]
	v_pk_mul_f32 v[62:63], v[62:63], v[220:221]
	v_pk_mul_f32 v[60:61], v[60:61], v[218:219]
	v_pk_mul_f32 v[66:67], v[66:67], v[220:221]
	v_pk_mul_f32 v[64:65], v[64:65], v[218:219]
	v_pk_mul_f32 v[70:71], v[70:71], v[220:221]
	v_pk_mul_f32 v[68:69], v[68:69], v[218:219]
	s_waitcnt lgkmcnt(1)
	v_mfma_f32_16x16x32_bf16 v[56:59], v[214:217], v[246:249], v[56:59]
	v_mfma_f32_16x16x32_bf16 v[60:63], v[214:217], v[166:169], v[60:63]
	v_mfma_f32_16x16x32_bf16 v[64:67], v[214:217], v[170:173], v[64:67]
	v_mfma_f32_16x16x32_bf16 v[68:71], v[214:217], v[174:177], v[68:71]
	s_waitcnt lgkmcnt(0)
	v_mfma_f32_16x16x32_bf16 v[56:59], v[222:225], v[182:185], v[56:59]
	v_mfma_f32_16x16x32_bf16 v[60:63], v[222:225], v[80:83], v[60:63]
	v_mfma_f32_16x16x32_bf16 v[64:67], v[222:225], v[84:87], v[64:67]
	v_mfma_f32_16x16x32_bf16 v[68:71], v[222:225], v[88:91], v[68:71]
	s_and_saveexec_b64 s[64:65], vcc
	s_cbranch_execz .LBB0_303
	v_add_u32_e32 v18, s88, v132
	v_ashrrev_i32_e32 v19, 31, v18
	v_lshlrev_b64 v[18:19], 12, v[18:19]
	v_lshl_add_u64 v[18:19], s[26:27], 0, v[18:19]
	s_lshl_b32 s70, s91, 10
	s_mov_b32 s71, s12
	v_lshl_add_u64 v[18:19], v[18:19], 0, s[70:71]
	s_lshl_b32 s70, s90, 7
	v_lshl_add_u64 v[18:19], v[18:19], 0, s[70:71]
	v_mov_b32_e32 v113, v17
	v_lshl_add_u64 v[18:19], v[18:19], 0, v[112:113]
	v_mov_b32_e32 v115, v17
	v_cvt_pk_bf16_f32 v72, v72, v73
	v_cvt_pk_bf16_f32 v73, v74, v75
	v_lshl_add_u64 v[18:19], v[18:19], 0, v[114:115]
	global_store_dwordx2 v[18:19], v[72:73], off
	v_cvt_pk_bf16_f32 v72, v76, v77
	v_cvt_pk_bf16_f32 v73, v78, v79
	global_store_dwordx2 v[18:19], v[72:73], off offset:32

; template <int DK, int DV, bool SEPQ> ...
;     ...
;         const float gi_i = GI[16 * m + fr];
;         const int n0 = 2 * hw, n1 = 2 * hw + 1; const bool do0 = n0 <= m, do1 = n1 <= m;
;         f32x4 acc0 = {0.f, 0.f, 0.f, 0.f}, acc1 = {0.f, 0.f, 0.f, 0.f};
; #pragma unroll
;         for (int vt = 0; vt < NVTW; ++vt) O[vt] = (f32x4){0.f, 0.f, 0.f, 0.f};
; #pragma unroll
;         for (int ks = 0; ks < DK / 32; ++ks) {
;             const bf16x8 qf = *(const bf16x8*)(QA + (16 * m + fr) * LQ + 32 * ks + 8 * fq);
;             if (do0) { const bf16x8 kf = *(const bf16x8*)(KB + (16 * n0 + fr) * LQ + 32 * ks + 8 * fq); acc0 = __builtin_amdgcn_mfma_f32_16x16x32_bf16(kf, qf, acc0, 0, 0, 0); }
;             if (do1) { const bf16x8 kf = *(const bf16x8*)(KB + (16 * n1 + fr) * LQ + 32 * ks + 8 * fq); acc1 = __builtin_amdgcn_mfma_f32_16x16x32_bf16(kf, qf, acc1, 0, 0, 0); }
;             bf16x8 qs = qf; if (SEPQ) qs = *(const bf16x8*)(QS + (16 * m + fr) * LQ + 32 * ks + 8 * fq);
; #pragma unroll
;             for (int vt = 0; vt < NVTW; ++vt) { const bf16x8 sf = *(const bf16x8*)(ST + (16 * (hw * NVTW + vt) + fr) * LQ + 32 * ks + 8 * fq); O[vt] = __builtin_amdgcn_mfma_f32_16x16x32_bf16(sf, qs, O[vt], 0, 0, 0); }
;         }
; #pragma unroll
;         for (int nn = 0; nn < 2; ++nn) {
;             const int n = 2 * hw + nn; const f32x4 acc = nn == 0 ? acc0 : acc1;
;             const f32x4 gj = *(const f32x4*)(GI + 16 * n + 4 * fq); const int i = 16 * m + fr, j0 = 16 * n + 4 * fq; float p[4];
; #pragma unroll
;             for (int e = 0; e < 4; ++e) p[e] = (j0 + e <= i) ? acc[e] * __expf(gi_i - gj[e]) : 0.f;
;             u32x2 w; w.x = cvt_pk_bf16(p[0], p[1]); w.y = cvt_pk_bf16(p[2], p[3]); *(u32x2*)(P + (16 * m + fr) * LJ + j0) = w;
;         }
;         const float ei = __expf(gi_i);
; #pragma unroll
;         for (int vt = 0; vt < NVTW; ++vt) O[vt] = O[vt] * ei;
; __device__ __forceinline__ void mamba_block(ArgsP a_, unsigned char* smem) { const ArgsP a = a_;
;     ...
;         if (i < len) { const float Dh = AIN(24)[hd];
; #pragma unroll
;             for (int vt = 0; vt < 2; ++vt) { const int v = 16 * (hw * 2 + vt) + 4 * fq; const size_t o = (size_t)(row0 + i) * 2048 + hd * 64 + v;
;                 const u32x2 xt = *(const u32x2*)(XC + (size_t)(row0 + i) * 4096 + hd * 64 + v); const u32x2 zt = *(const u32x2*)(ZG + o);
.LBB0_356:
	s_load_dwordx2 s[22:23], s[4:5], 0xc0
	v_add_u32_e32 v212, s72, v71
	v_ashrrev_i32_e32 v213, 31, v212
	v_lshlrev_b64 v[214:215], 11, v[212:213]
	v_lshlrev_b64 v[212:213], 13, v[212:213]
	v_readlane_b32 s74, v255, 12
	v_readlane_b32 s75, v255, 13
	v_lshl_or_b32 v216, s71, 6, v214
	v_or_b32_e32 v214, v216, v66
	s_nop 0
	v_lshl_add_u64 v[212:213], s[74:75], 0, v[212:213]
	s_lshl_b32 s74, s71, 7
	s_mov_b32 s75, s12
	v_lshl_add_u64 v[212:213], v[212:213], 0, s[74:75]
	v_lshlrev_b32_e32 v218, 1, v66
	v_mov_b32_e32 v219, 0
	v_lshl_add_u64 v[212:213], v[212:213], 0, v[218:219]
	v_lshlrev_b64 v[218:219], 1, v[214:215]
	global_load_dwordx2 v[202:203], v[212:213], off
	v_lshl_add_u64 v[218:219], s[24:25], 0, v[218:219]
	global_load_dwordx2 v[204:205], v[218:219], off
	global_load_dwordx2 v[206:207], v[212:213], off offset:32
	v_or_b32_e32 v214, v216, v68
	v_lshlrev_b64 v[218:219], 1, v[214:215]
	v_lshl_add_u64 v[218:219], s[24:25], 0, v[218:219]
	global_load_dwordx2 v[208:209], v[218:219], off
	s_lshl_b32 s74, s71, 2
	v_mov_b32_e32 v217, s74
	s_waitcnt lgkmcnt(0)
	global_load_dword v210, v217, s[22:23]
	s_waitcnt lgkmcnt(0)
	ds_read_b128 v[130:133], v82
	ds_read_b128 v[134:137], v82 offset:64
	ds_read_b32 v123, v81
	ds_read_b128 v[220:223], v64
	ds_read_b128 v[224:227], v65 offset:17408
	ds_read_b128 v[228:231], v65 offset:21760
	ds_read_b128 v[232:235], v114
	ds_read_b128 v[236:239], v114 offset:4352
	ds_read_b128 v[164:167], v64 offset:64
	ds_read_b128 v[168:171], v65 offset:17472
	ds_read_b128 v[172:175], v65 offset:21824
	ds_read_b128 v[176:179], v114 offset:64
	ds_read_b128 v[180:183], v114 offset:4416
	s_waitcnt lgkmcnt(5)
	v_mfma_f32_16x16x32_bf16 v[40:43], v[224:227], v[220:223], 0
	v_mfma_f32_16x16x32_bf16 v[36:39], v[228:231], v[220:223], 0
	v_mfma_f32_16x16x32_bf16 v[44:47], v[232:235], v[220:223], 0
	v_mfma_f32_16x16x32_bf16 v[48:51], v[236:239], v[220:223], 0
	ds_read_b128 v[220:223], v64 offset:128
	ds_read_b128 v[224:227], v65 offset:17536
	ds_read_b128 v[228:231], v65 offset:21888
	ds_read_b128 v[232:235], v114 offset:128
	ds_read_b128 v[236:239], v114 offset:4480
	s_waitcnt lgkmcnt(5)
	v_mfma_f32_16x16x32_bf16 v[40:43], v[168:171], v[164:167], v[40:43]
	v_mfma_f32_16x16x32_bf16 v[36:39], v[172:175], v[164:167], v[36:39]
	v_mfma_f32_16x16x32_bf16 v[44:47], v[176:179], v[164:167], v[44:47]
	v_mfma_f32_16x16x32_bf16 v[48:51], v[180:183], v[164:167], v[48:51]
	ds_read_b128 v[164:167], v64 offset:192
	ds_read_b128 v[168:171], v65 offset:17600
	ds_read_b128 v[172:175], v65 offset:21952
	ds_read_b128 v[176:179], v114 offset:192
	ds_read_b128 v[180:183], v114 offset:4544
	s_waitcnt lgkmcnt(5)
	v_mfma_f32_16x16x32_bf16 v[40:43], v[224:227], v[220:223], v[40:43]
	v_mfma_f32_16x16x32_bf16 v[36:39], v[228:231], v[220:223], v[36:39]
	v_mfma_f32_16x16x32_bf16 v[44:47], v[232:235], v[220:223], v[44:47]
	v_mfma_f32_16x16x32_bf16 v[48:51], v[236:239], v[220:223], v[48:51]
	s_waitcnt lgkmcnt(0)
	v_mfma_f32_16x16x32_bf16 v[40:43], v[168:171], v[164:167], v[40:43]
	v_mfma_f32_16x16x32_bf16 v[36:39], v[172:175], v[164:167], v[36:39]
	v_mfma_f32_16x16x32_bf16 v[44:47], v[176:179], v[164:167], v[44:47]
	v_mfma_f32_16x16x32_bf16 v[48:51], v[180:183], v[164:167], v[48:51]
	s_nop 7
	v_cmp_gt_i32_e32 vcc, s73, v71
	v_sub_f32_e32 v16, v123, v130
	v_mul_f32_e32 v16, 0x3fb8aa3b, v16
	v_exp_f32_e32 v16, v16
	v_sub_f32_e32 v18, v123, v131
	v_sub_f32_e32 v19, v123, v132
	v_mul_f32_e32 v18, 0x3fb8aa3b, v18
	v_mul_f32_e32 v16, v40, v16
	v_mul_f32_e32 v19, 0x3fb8aa3b, v19
	v_sub_f32_e32 v40, v123, v133
	v_exp_f32_e32 v18, v18
	v_exp_f32_e32 v19, v19
	v_mul_f32_e32 v40, 0x3fb8aa3b, v40
	v_exp_f32_e32 v40, v40
	v_mul_f32_e32 v18, v41, v18
	v_mul_f32_e32 v19, v42, v19
	v_cndmask_b32_e64 v18, 0, v18, s[48:49]
	v_cndmask_b32_e64 v19, v19, 0, s[50:51]
	v_mul_f32_e32 v40, v43, v40
	v_cndmask_b32_e64 v16, v16, 0, s[46:47]
	v_cndmask_b32_e64 v40, v40, 0, s[52:53]
	v_cvt_pk_bf16_f32 v18, v16, v18
	v_cvt_pk_bf16_f32 v19, v19, v40
	ds_write_b64 v83, v[18:19]
	v_sub_f32_e32 v16, v123, v134
	v_mul_f32_e32 v16, 0x3fb8aa3b, v16
	v_sub_f32_e32 v18, v123, v135
	v_exp_f32_e32 v16, v16
	v_mul_f32_e32 v18, 0x3fb8aa3b, v18
	v_exp_f32_e32 v18, v18
	v_sub_f32_e32 v19, v123, v136
	v_mul_f32_e32 v16, v36, v16
	v_sub_f32_e32 v36, v123, v137
	v_mul_f32_e32 v18, v37, v18
	v_mul_f32_e32 v19, 0x3fb8aa3b, v19
	v_mul_f32_e32 v36, 0x3fb8aa3b, v36
	v_cndmask_b32_e64 v16, v16, 0, s[54:55]
	v_cndmask_b32_e64 v18, 0, v18, s[56:57]
	v_exp_f32_e32 v19, v19
	v_exp_f32_e32 v36, v36
	v_cvt_pk_bf16_f32 v18, v16, v18
	v_mul_f32_e32 v16, 0x3fb8aa3b, v123
	v_exp_f32_e32 v16, v16
	v_mul_f32_e32 v19, v38, v19
	v_mul_f32_e32 v36, v39, v36
	v_cndmask_b32_e64 v19, v19, 0, s[58:59]
	v_cndmask_b32_e64 v36, v36, 0, s[60:61]
	v_cvt_pk_bf16_f32 v19, v19, v36
	ds_write_b64 v83, v[18:19] offset:32
	v_pk_mul_f32 v[36:37], v[16:17], v[44:45] op_sel_hi:[0,1]
	v_pk_mul_f32 v[38:39], v[16:17], v[46:47] op_sel_hi:[0,1]
	v_pk_mul_f32 v[40:41], v[16:17], v[48:49] op_sel_hi:[0,1]
	v_pk_mul_f32 v[42:43], v[16:17], v[50:51] op_sel_hi:[0,1]
	s_waitcnt lgkmcnt(0)
	s_barrier
; __device__ __forceinline__ unsigned cvt_pk_bf16(float lo, float hi) { unsigned r; asm("v_cvt_pk_bf16_f32 %0, %1, %2" : "=v"(r) : "v"(lo), "v"(hi)); return r; }
; template <int DK, int DV, bool SEPQ> ...
;     ...
; #pragma unroll
;     for (int ks = 0; ks < 2; ++ks) { const bf16x8 pf = *(const bf16x8*)(P + (16 * m + fr) * LJ + 32 * ks + 8 * fq);
; #pragma unroll
;         for (int vt = 0; vt < NVTW; ++vt) { const bf16x8 vf = *(const bf16x8*)(VT + (16 * (hw * NVTW + vt) + fr) * LJ + 32 * ks + 8 * fq); O[vt] = __builtin_amdgcn_mfma_f32_16x16x32_bf16(vf, pf, O[vt], 0, 0, 0); } }
; #pragma unroll
;     for (int ct = 0; ct < NCTW; ++ct) { const int ctg = wid * NCTW + ct; const f32x4 dec = *(const f32x4*)(SDEC + 16 * ctg + 4 * fq);
; #pragma unroll
;         for (int vt = 0; vt < NVT; ++vt) S[ct][vt] = S[ct][vt] * dec;
; #pragma unroll
;         for (int ks = 0; ks < 2; ++ks) { const bf16x8 kf = *(const bf16x8*)(KT + (16 * ctg + fr) * LJ + 32 * ks + 8 * fq);
; #pragma unroll
;             for (int vt = 0; vt < NVT; ++vt) { const bf16x8 vf = *(const bf16x8*)(VT2 + (16 * vt + fr) * LJ + 32 * ks + 8 * fq); S[ct][vt] = __builtin_amdgcn_mfma_f32_16x16x32_bf16(kf, vf, S[ct][vt], 0, 0, 0); } } }
; __device__ __forceinline__ void mamba_block(ArgsP a_, unsigned char* smem) { const ArgsP a = a_;
;     ...
;         if (i < len) { const float Dh = AIN(24)[hd];
; #pragma unroll
;             for (int vt = 0; vt < 2; ++vt) { const int v = 16 * (hw * 2 + vt) + 4 * fq; const size_t o = (size_t)(row0 + i) * 2048 + hd * 64 + v;
;                 const u32x2 xt = *(const u32x2*)(XC + (size_t)(row0 + i) * 4096 + hd * 64 + v); const u32x2 zt = *(const u32x2*)(ZG + o);
;                 const f32x4 xs = {__uint_as_float(xt.x << 16), __uint_as_float(xt.x & 0xffff0000u), __uint_as_float(xt.y << 16), __uint_as_float(xt.y & 0xffff0000u)};
;                 const f32x4 zg = {__uint_as_float(zt.x << 16), __uint_as_float(zt.x & 0xffff0000u), __uint_as_float(zt.y << 16), __uint_as_float(zt.y & 0xffff0000u)};
;                 const f32x4 y = (O[vt] + xs * Dh) * zg; *(u32x2*)(YB + o) = (u32x2){cvt_pk_bf16(y[0], y[1]), cvt_pk_bf16(y[2], y[3])}; } }
	ds_read_b128 v[220:223], v84
	ds_read_b128 v[224:227], v110 offset:53248
	ds_read_b128 v[228:231], v110 offset:55552
	ds_read_b128 v[232:235], v84 offset:64
	ds_read_b128 v[236:239], v110 offset:53312
	ds_read_b128 v[240:243], v110 offset:55616
	ds_read_b128 v[244:247], v111
	ds_read_b128 v[248:251], v70 offset:34816
	ds_read_b128 v[164:167], v112 offset:62464
	ds_read_b128 v[168:171], v112 offset:64768
	ds_read_b128 v[172:175], v113 offset:62464
	ds_read_b128 v[176:179], v113 offset:64768
	ds_read_b128 v[180:183], v70 offset:34880
	s_waitcnt lgkmcnt(11)
	v_mfma_f32_16x16x32_bf16 v[36:39], v[224:227], v[220:223], v[36:39]
	ds_read_b128 v[224:227], v112 offset:62528
	s_waitcnt lgkmcnt(11)
	v_mfma_f32_16x16x32_bf16 v[44:47], v[228:231], v[220:223], v[40:43]
	ds_read_b128 v[220:223], v112 offset:64832
	ds_read_b128 v[228:231], v113 offset:62528
	s_nop 1
	s_waitcnt lgkmcnt(11)
	v_mfma_f32_16x16x32_bf16 v[40:43], v[236:239], v[232:235], v[36:39]
	ds_read_b128 v[236:239], v113 offset:64832
	s_nop 2
	s_waitcnt lgkmcnt(11)
	v_mfma_f32_16x16x32_bf16 v[36:39], v[240:243], v[232:235], v[44:47]
	s_nop 2
	s_waitcnt lgkmcnt(10)
	v_pk_mul_f32 v[22:23], v[22:23], v[246:247]
	v_pk_mul_f32 v[20:21], v[20:21], v[244:245]
	v_pk_mul_f32 v[24:25], v[24:25], v[244:245]
	v_pk_mul_f32 v[26:27], v[26:27], v[246:247]
	v_pk_mul_f32 v[28:29], v[28:29], v[244:245]
	v_pk_mul_f32 v[30:31], v[30:31], v[246:247]
	v_pk_mul_f32 v[32:33], v[32:33], v[244:245]
	v_pk_mul_f32 v[34:35], v[34:35], v[246:247]
	s_waitcnt lgkmcnt(8)
	v_mfma_f32_16x16x32_bf16 v[18:21], v[248:251], v[164:167], v[20:23]
	s_waitcnt lgkmcnt(7)
	v_mfma_f32_16x16x32_bf16 v[24:27], v[248:251], v[168:171], v[24:27]
	s_waitcnt lgkmcnt(6)
	v_mfma_f32_16x16x32_bf16 v[28:31], v[248:251], v[172:175], v[28:31]
	s_waitcnt lgkmcnt(5)
	v_mfma_f32_16x16x32_bf16 v[32:35], v[248:251], v[176:179], v[32:35]
	s_waitcnt lgkmcnt(3)
	v_mfma_f32_16x16x32_bf16 v[20:23], v[180:183], v[224:227], v[18:21]
	s_waitcnt lgkmcnt(2)
	v_mfma_f32_16x16x32_bf16 v[24:27], v[180:183], v[220:223], v[24:27]
	s_waitcnt lgkmcnt(1)
	v_mfma_f32_16x16x32_bf16 v[28:31], v[180:183], v[228:231], v[28:31]
	s_waitcnt lgkmcnt(0)
	v_mfma_f32_16x16x32_bf16 v[32:35], v[180:183], v[236:239], v[32:35]
	s_and_saveexec_b64 s[74:75], vcc
	s_cbranch_execz .LBB0_374
	v_add_u32_e32 v44, s72, v71
	v_ashrrev_i32_e32 v45, 31, v44
	s_waitcnt vmcnt(0)
	v_mov_b32_e32 v18, v210
	v_readlane_b32 s22, v255, 12
	v_lshlrev_b64 v[46:47], 11, v[44:45]
	v_lshlrev_b64 v[44:45], 13, v[44:45]
	v_readlane_b32 s23, v255, 13
	v_lshl_or_b32 v19, s71, 6, v46
	v_or_b32_e32 v46, v19, v66
	v_lshl_add_u64 v[44:45], s[22:23], 0, v[44:45]
	s_lshl_b32 s22, s71, 7
	s_mov_b32 s23, s12
	v_lshl_add_u64 v[44:45], v[44:45], 0, s[22:23]
	v_lshlrev_b32_e32 v16, 1, v66
	v_lshl_add_u64 v[44:45], v[44:45], 0, v[16:17]
	v_lshlrev_b64 v[50:51], 1, v[46:47]
	v_mov_b32_e32 v48, v202
	v_mov_b32_e32 v49, v203
	v_lshl_add_u64 v[52:53], s[24:25], 0, v[50:51]
	v_mov_b32_e32 v52, v204
	v_mov_b32_e32 v53, v205
	v_or_b32_e32 v46, v19, v68
	v_lshlrev_b32_e32 v54, 16, v48
	v_and_b32_e32 v55, 0xffff0000, v48
	v_lshlrev_b32_e32 v48, 16, v49
	v_and_b32_e32 v49, 0xffff0000, v49
	v_lshlrev_b32_e32 v124, 16, v52
	v_and_b32_e32 v125, 0xffff0000, v52
	v_lshlrev_b32_e32 v52, 16, v53
	v_and_b32_e32 v53, 0xffff0000, v53
	v_pk_fma_f32 v[40:41], v[18:19], v[54:55], v[40:41] op_sel_hi:[0,1,1]
	v_pk_fma_f32 v[42:43], v[18:19], v[48:49], v[42:43] op_sel_hi:[0,1,1]
	v_pk_mul_f32 v[42:43], v[42:43], v[52:53]
	v_pk_mul_f32 v[40:41], v[40:41], v[124:125]
	s_nop 0
	v_cvt_pk_bf16_f32 v40, v40, v41
	v_cvt_pk_bf16_f32 v41, v42, v43
	v_lshl_add_u64 v[42:43], s[26:27], 0, v[50:51]
	global_store_dwordx2 v[42:43], v[40:41], off
	v_lshlrev_b64 v[42:43], 1, v[46:47]
	v_mov_b32_e32 v40, v206
	v_mov_b32_e32 v41, v207
	v_lshl_add_u64 v[44:45], s[24:25], 0, v[42:43]
	v_mov_b32_e32 v44, v208
	v_mov_b32_e32 v45, v209
	v_lshlrev_b32_e32 v46, 16, v40
	v_and_b32_e32 v47, 0xffff0000, v40
	v_lshlrev_b32_e32 v40, 16, v41
	v_and_b32_e32 v41, 0xffff0000, v41
	v_lshlrev_b32_e32 v48, 16, v44
	v_and_b32_e32 v49, 0xffff0000, v44
	v_lshlrev_b32_e32 v44, 16, v45
	v_and_b32_e32 v45, 0xffff0000, v45
	v_pk_fma_f32 v[36:37], v[18:19], v[46:47], v[36:37] op_sel_hi:[0,1,1]
	v_pk_fma_f32 v[18:19], v[18:19], v[40:41], v[38:39] op_sel_hi:[0,1,1]
	v_pk_mul_f32 v[18:19], v[18:19], v[44:45]
	v_pk_mul_f32 v[36:37], v[36:37], v[48:49]
	s_nop 0
	v_cvt_pk_bf16_f32 v36, v36, v37
	v_cvt_pk_bf16_f32 v37, v18, v19
	v_lshl_add_u64 v[18:19], s[26:27], 0, v[42:43]
	global_store_dwordx2 v[18:19], v[36:37], off
